# ffn-in GEMM: paired 256-row tiles sharing the weight tile (same scheme as gemm1), second epilogue pass for the lower tile
# speedup vs baseline: 1.0123x; 1.0044x over previous
.LBB0_189:
	s_andn2_b64 vcc, exec, s[4:5]
	s_cbranch_vccnz .LBB0_194
	s_cmpk_gt_i32 s71, 0x57f
	s_cbranch_scc1 .LBB0_194
	s_mov_b64 s[30:31], s[12:13]
	s_mul_hi_i32 s4, s22, 0x2580000
	s_mul_i32 s5, s22, 0x2580000
	v_readlane_b32 s12, v252, 4
	v_readlane_b32 s26, v252, 18
	v_readlane_b32 s20, v252, 12
	v_readlane_b32 s27, v252, 19
	s_add_u32 s5, s26, s5
	s_addc_u32 s20, s27, s4
	v_readlane_b32 s18, v252, 10
	v_readlane_b32 s21, v252, 13
	v_readlane_b32 s22, v252, 14
	s_add_u32 s4, s5, 0x1500000
	s_mov_b32 s18, 0x10000
	s_addc_u32 s5, s20, 0
	s_lshl_b32 s20, s71, 6
	s_lshl_b32 s21, s81, 6
	s_mov_b32 s22, s71
	s_movk_i32 s26, 0xb00
	s_movk_i32 s27, 0x48
	s_movk_i32 s28, 0x90
	s_mov_b32 s29, 0x20000
	v_readlane_b32 s13, v252, 5
	v_readlane_b32 s14, v252, 6
	v_readlane_b32 s15, v252, 7
	v_readlane_b32 s16, v252, 8
	v_readlane_b32 s17, v252, 9
	v_readlane_b32 s19, v252, 11
	v_readlane_b32 s23, v252, 15
	v_readlane_b32 s24, v252, 16
	v_readlane_b32 s25, v252, 17
.LBB0_192:
	v_mov_b32_e32 v0, v1
	s_mul_hi_i32 s23, s22, 0x2e8ba2e9
	v_mbcnt_lo_u32_b32 v0, -1, v0
	v_mbcnt_hi_u32_b32 v0, -1, v0
	s_lshr_b32 s24, s23, 31
	s_ashr_i32 s23, s23, 3
	v_add_u32_e32 v90, s80, v0
	s_add_i32 s23, s23, s24
	s_mov_b32 s98, s23
	s_mul_i32 s24, s98, 44
	s_sub_i32 s25, s22, s24
	s_lshl_b32 s23, s98, 1
	s_add_i32 s24, s22, s24
	s_lshl_b32 s99, s24, 6
	s_lshl_b32 s25, s25, 6
	s_lshl_b32 s24, s23, 7
	v_lshlrev_b32_e32 v0, 3, v90
	v_ashrrev_i32_e32 v89, 3, v90
	v_and_b32_e32 v88, 56, v0
	s_waitcnt lgkmcnt(0)
	v_lshrrev_b32_e32 v84, 2, v90
	v_lshrrev_b32_e32 v85, 6, v90
	v_lshl_add_u32 v84, v85, 4, v84
	v_bfe_u32 v85, v90, 4, 2
	v_and_b32_e32 v86, 3, v90
	v_xor_b32_e32 v85, v85, v86
	v_lshlrev_b32_e32 v85, 4, v85
	v_add_u32_e32 v86, s24, v84
	v_lshl_or_b32 v66, v86, 11, v85
	v_add_u32_e32 v68, 0x8000, v66
	v_add_u32_e32 v70, 0x40000, v66
	v_add_u32_e32 v72, 0x48000, v66
	s_lshr_b32 vcc_lo, s80, 6
	s_and_b32 vcc_hi, vcc_lo, 1
	s_mul_i32 vcc_hi, vcc_hi, 0xb00
	s_lshr_b32 vcc_lo, vcc_lo, 1
	s_lshl_b32 vcc_lo, vcc_lo, 5
	s_add_i32 vcc_lo, vcc_lo, vcc_hi
	s_add_i32 vcc_lo, vcc_lo, s25
	v_bfe_u32 v86, v90, 2, 4
	v_add_u32_e32 v86, vcc_lo, v86
	v_lshl_or_b32 v74, v86, 11, v85
	v_add_u32_e32 v76, 0x8000, v74
	v_mov_b32_e32 v67, 0
	v_mov_b32_e32 v69, 0
	v_mov_b32_e32 v71, 0
	v_mov_b32_e32 v73, 0
	v_mov_b32_e32 v75, 0
	v_mov_b32_e32 v77, 0
	v_lshl_add_u64 v[66:67], v[66:67], 0, s[72:73]
	v_lshl_add_u64 v[68:69], v[68:69], 0, s[72:73]
	v_lshl_add_u64 v[70:71], v[70:71], 0, s[72:73]
	v_lshl_add_u64 v[72:73], v[72:73], 0, s[72:73]
	v_lshl_add_u64 v[74:75], v[74:75], 0, s[4:5]
	v_lshl_add_u64 v[76:77], v[76:77], 0, s[4:5]
	v_mov_b32_e32 v84, 64
	v_mov_b32_e32 v85, 0
	v_lshl_add_u64 v[126:127], v[66:67], 0, v[84:85]
	v_lshl_add_u64 v[128:129], v[68:69], 0, v[84:85]
	v_lshl_add_u64 v[130:131], v[70:71], 0, v[84:85]
	v_lshl_add_u64 v[132:133], v[72:73], 0, v[84:85]
	v_lshl_add_u64 v[244:245], v[74:75], 0, v[84:85]
	v_lshl_add_u64 v[246:247], v[76:77], 0, v[84:85]
	v_bfe_u32 v84, v90, 5, 1
	v_bfe_u32 v85, v90, 2, 2
	v_xor_b32_e32 v84, v84, v85
	v_lshlrev_b32_e32 v84, 4, v84
	v_lshrrev_b32_e32 v85, 1, v90
	v_and_b32_e32 v85, 64, v85
	v_and_b32_e32 v86, 31, v90
	v_or_b32_e32 v85, v85, v86
	v_lshl_or_b32 v78, v85, 6, v84
	v_xor_b32_e32 v79, 32, v78
	v_and_b32_e32 v85, 0x5f, v90
	v_lshl_or_b32 v80, v85, 6, v84
	v_add_u32_e32 v80, 0x4000, v80
	v_xor_b32_e32 v81, 32, v80
	v_mov_b32_e32 v82, 0x80
	v_mov_b32_e32 v83, 0
	s_lshl_b32 vcc_lo, s80, 5
	v_ashrrev_i32_e32 v2, 1, v90
	v_and_b32_e32 v91, 0xffffffc0, v2
	v_and_b32_e32 v0, 31, v90
	v_mov_b32_e32 v34, 0
	v_mov_b32_e32 v35, 0
	v_mov_b32_e32 v36, 0
	v_mov_b32_e32 v37, 0
	v_mov_b32_e32 v38, 0
	v_mov_b32_e32 v39, 0
	v_mov_b32_e32 v40, 0
	v_mov_b32_e32 v41, 0
	v_mov_b32_e32 v42, 0
	v_mov_b32_e32 v43, 0
	v_mov_b32_e32 v44, 0
	v_mov_b32_e32 v45, 0
	v_mov_b32_e32 v46, 0
	v_mov_b32_e32 v47, 0
	v_mov_b32_e32 v48, 0
	v_mov_b32_e32 v49, 0
	v_mov_b32_e32 v50, 0
	v_mov_b32_e32 v51, 0
	v_mov_b32_e32 v52, 0
	v_mov_b32_e32 v53, 0
	v_mov_b32_e32 v54, 0
	v_mov_b32_e32 v55, 0
	v_mov_b32_e32 v56, 0
	v_mov_b32_e32 v57, 0
	v_mov_b32_e32 v58, 0
	v_mov_b32_e32 v59, 0
	v_mov_b32_e32 v60, 0
	v_mov_b32_e32 v61, 0
	v_mov_b32_e32 v62, 0
	v_mov_b32_e32 v63, 0
	v_mov_b32_e32 v64, 0
	v_mov_b32_e32 v65, 0
	v_mov_b32_e32 v2, 0
	v_mov_b32_e32 v3, 0
	v_mov_b32_e32 v4, 0
	v_mov_b32_e32 v5, 0
	v_mov_b32_e32 v6, 0
	v_mov_b32_e32 v7, 0
	v_mov_b32_e32 v8, 0
	v_mov_b32_e32 v9, 0
	v_mov_b32_e32 v10, 0
	v_mov_b32_e32 v11, 0
	v_mov_b32_e32 v12, 0
	v_mov_b32_e32 v13, 0
	v_mov_b32_e32 v14, 0
	v_mov_b32_e32 v15, 0
	v_mov_b32_e32 v16, 0
	v_mov_b32_e32 v17, 0
	v_mov_b32_e32 v18, 0
	v_mov_b32_e32 v19, 0
	v_mov_b32_e32 v20, 0
	v_mov_b32_e32 v21, 0
	v_mov_b32_e32 v22, 0
	v_mov_b32_e32 v23, 0
	v_mov_b32_e32 v24, 0
	v_mov_b32_e32 v25, 0
	v_mov_b32_e32 v26, 0
	v_mov_b32_e32 v27, 0
	v_mov_b32_e32 v28, 0
	v_mov_b32_e32 v29, 0
	v_mov_b32_e32 v30, 0
	v_mov_b32_e32 v31, 0
	v_mov_b32_e32 v32, 0
	v_mov_b32_e32 v33, 0
	v_mov_b32_e32 v94, 0
	v_mov_b32_e32 v95, 0
	v_mov_b32_e32 v96, 0
	v_mov_b32_e32 v97, 0
	v_mov_b32_e32 v98, 0
	v_mov_b32_e32 v99, 0
	v_mov_b32_e32 v100, 0
	v_mov_b32_e32 v101, 0
	v_mov_b32_e32 v102, 0
	v_mov_b32_e32 v103, 0
	v_mov_b32_e32 v104, 0
	v_mov_b32_e32 v105, 0
	v_mov_b32_e32 v106, 0
	v_mov_b32_e32 v107, 0
	v_mov_b32_e32 v108, 0
	v_mov_b32_e32 v109, 0
	v_mov_b32_e32 v110, 0
	v_mov_b32_e32 v111, 0
	v_mov_b32_e32 v112, 0
	v_mov_b32_e32 v113, 0
	v_mov_b32_e32 v114, 0
	v_mov_b32_e32 v115, 0
	v_mov_b32_e32 v116, 0
	v_mov_b32_e32 v117, 0
	v_mov_b32_e32 v118, 0
	v_mov_b32_e32 v119, 0
	v_mov_b32_e32 v120, 0
	v_mov_b32_e32 v121, 0
	v_mov_b32_e32 v122, 0
	v_mov_b32_e32 v123, 0
	v_mov_b32_e32 v124, 0
	v_mov_b32_e32 v125, 0
	v_mov_b32_e32 v134, 0
	v_mov_b32_e32 v135, 0
	v_mov_b32_e32 v136, 0
	v_mov_b32_e32 v137, 0
	v_mov_b32_e32 v138, 0
	v_mov_b32_e32 v139, 0
	v_mov_b32_e32 v140, 0
	v_mov_b32_e32 v141, 0
	v_mov_b32_e32 v142, 0
	v_mov_b32_e32 v143, 0
	v_mov_b32_e32 v144, 0
	v_mov_b32_e32 v145, 0
	v_mov_b32_e32 v146, 0
	v_mov_b32_e32 v147, 0
	v_mov_b32_e32 v148, 0
	v_mov_b32_e32 v149, 0
	v_mov_b32_e32 v150, 0
	v_mov_b32_e32 v151, 0
	v_mov_b32_e32 v152, 0
	v_mov_b32_e32 v153, 0
	v_mov_b32_e32 v154, 0
	v_mov_b32_e32 v155, 0
	v_mov_b32_e32 v156, 0
	v_mov_b32_e32 v157, 0
	v_mov_b32_e32 v158, 0
	v_mov_b32_e32 v159, 0
	v_mov_b32_e32 v160, 0
	v_mov_b32_e32 v161, 0
	v_mov_b32_e32 v162, 0
	v_mov_b32_e32 v163, 0
	v_mov_b32_e32 v164, 0
	v_mov_b32_e32 v165, 0
	s_barrier
	s_mov_b32 m0, vcc_lo
	s_nop 0
	global_load_lds_dwordx4 v[66:67], off
	s_add_u32 m0, vcc_lo, 0x6000
	s_nop 0
	global_load_lds_dwordx4 v[126:127], off
	s_add_u32 m0, vcc_lo, 0x400
	s_nop 0
	global_load_lds_dwordx4 v[68:69], off
	s_add_u32 m0, vcc_lo, 0x6400
	s_nop 0
	global_load_lds_dwordx4 v[128:129], off
	s_add_u32 m0, vcc_lo, 0x2000
	s_nop 0
	global_load_lds_dwordx4 v[70:71], off
	s_add_u32 m0, vcc_lo, 0x8000
	s_nop 0
	global_load_lds_dwordx4 v[130:131], off
	s_add_u32 m0, vcc_lo, 0x2400
	s_nop 0
	global_load_lds_dwordx4 v[72:73], off
	s_add_u32 m0, vcc_lo, 0x8400
	s_nop 0
	global_load_lds_dwordx4 v[132:133], off
	s_add_u32 m0, vcc_lo, 0x4000
	s_nop 0
	global_load_lds_dwordx4 v[74:75], off
	s_add_u32 m0, vcc_lo, 0xa000
	s_nop 0
	global_load_lds_dwordx4 v[244:245], off
	s_add_u32 m0, vcc_lo, 0x4400
	s_nop 0
	global_load_lds_dwordx4 v[76:77], off
	s_add_u32 m0, vcc_lo, 0xa400
	s_nop 0
	global_load_lds_dwordx4 v[246:247], off
	v_lshl_add_u64 v[66:67], v[66:67], 0, v[82:83]
	v_lshl_add_u64 v[68:69], v[68:69], 0, v[82:83]
	v_lshl_add_u64 v[70:71], v[70:71], 0, v[82:83]
	v_lshl_add_u64 v[72:73], v[72:73], 0, v[82:83]
	v_lshl_add_u64 v[74:75], v[74:75], 0, v[82:83]
	v_lshl_add_u64 v[76:77], v[76:77], 0, v[82:83]
	v_lshl_add_u64 v[126:127], v[126:127], 0, v[82:83]
	v_lshl_add_u64 v[128:129], v[128:129], 0, v[82:83]
	v_lshl_add_u64 v[130:131], v[130:131], 0, v[82:83]
	v_lshl_add_u64 v[132:133], v[132:133], 0, v[82:83]
	v_lshl_add_u64 v[244:245], v[244:245], 0, v[82:83]
	v_lshl_add_u64 v[246:247], v[246:247], 0, v[82:83]
	s_waitcnt vmcnt(0)
	s_barrier
	ds_read_b128 v[166:169], v78
	ds_read_b128 v[170:173], v80
	ds_read_b128 v[174:177], v80 offset:2048
	ds_read_b128 v[178:181], v78 offset:2048
	ds_read_b128 v[182:185], v78 offset:8192
	ds_read_b128 v[188:191], v78 offset:10240
	s_waitcnt lgkmcnt(4)
	v_mfma_f32_32x32x16_bf16 v[34:49], v[166:169], v[170:173], v[34:49]
	ds_read_b128 v[192:195], v79
	s_waitcnt lgkmcnt(4)
	v_mfma_f32_32x32x16_bf16 v[50:65], v[166:169], v[174:177], v[50:65]
	ds_read_b128 v[206:209], v81
	s_waitcnt lgkmcnt(4)
	v_mfma_f32_32x32x16_bf16 v[2:17], v[178:181], v[170:173], v[2:17]
	ds_read_b128 v[210:213], v81 offset:2048
	v_mfma_f32_32x32x16_bf16 v[18:33], v[178:181], v[174:177], v[18:33]
	ds_read_b128 v[222:225], v79 offset:2048
	s_waitcnt lgkmcnt(5)
	v_mfma_f32_32x32x16_bf16 v[94:109], v[182:185], v[170:173], v[94:109]
	ds_read_b128 v[236:239], v79 offset:8192
	v_mfma_f32_32x32x16_bf16 v[110:125], v[182:185], v[174:177], v[110:125]
	ds_read_b128 v[240:243], v79 offset:10240
	s_waitcnt lgkmcnt(6)
	v_mfma_f32_32x32x16_bf16 v[134:149], v[188:191], v[170:173], v[134:149]
	v_mfma_f32_32x32x16_bf16 v[150:165], v[188:191], v[174:177], v[150:165]
	s_waitcnt vmcnt(0) lgkmcnt(0)
	s_barrier
	s_mov_b32 vcc_hi, 4
.Lg_ffninp_loop:
	v_mfma_f32_32x32x16_bf16 v[34:49], v[192:195], v[206:209], v[34:49]
	s_add_u32 m0, vcc_lo, 0xc000
	ds_read_b128 v[166:169], v78 offset:24576
	global_load_lds_dwordx4 v[66:67], off
	v_mfma_f32_32x32x16_bf16 v[50:65], v[192:195], v[210:213], v[50:65]
	s_mov_b32 m0, vcc_lo
	ds_read_b128 v[170:173], v80 offset:24576
	global_load_lds_dwordx4 v[126:127], off
	v_mfma_f32_32x32x16_bf16 v[2:17], v[222:225], v[206:209], v[2:17]
	s_add_u32 m0, vcc_lo, 0xc400
	ds_read_b128 v[174:177], v80 offset:26624
	global_load_lds_dwordx4 v[68:69], off
	v_mfma_f32_32x32x16_bf16 v[18:33], v[222:225], v[210:213], v[18:33]
	s_add_u32 m0, vcc_lo, 0x400
	ds_read_b128 v[178:181], v78 offset:26624
	global_load_lds_dwordx4 v[128:129], off
	v_mfma_f32_32x32x16_bf16 v[94:109], v[236:239], v[206:209], v[94:109]
	s_add_u32 m0, vcc_lo, 0xe000
	ds_read_b128 v[182:185], v78 offset:32768
	global_load_lds_dwordx4 v[70:71], off
	v_mfma_f32_32x32x16_bf16 v[110:125], v[236:239], v[210:213], v[110:125]
	s_add_u32 m0, vcc_lo, 0x2000
	ds_read_b128 v[188:191], v78 offset:34816
	global_load_lds_dwordx4 v[130:131], off
	v_mfma_f32_32x32x16_bf16 v[134:149], v[240:243], v[206:209], v[134:149]
	s_add_u32 m0, vcc_lo, 0xe400
	s_nop 0
	global_load_lds_dwordx4 v[72:73], off
	v_mfma_f32_32x32x16_bf16 v[150:165], v[240:243], v[210:213], v[150:165]
	s_add_u32 m0, vcc_lo, 0x2400
	s_nop 0
	global_load_lds_dwordx4 v[132:133], off
	s_waitcnt lgkmcnt(4)
	v_mfma_f32_32x32x16_bf16 v[34:49], v[166:169], v[170:173], v[34:49]
	s_add_u32 m0, vcc_lo, 0x10000
	ds_read_b128 v[192:195], v79 offset:24576
	global_load_lds_dwordx4 v[74:75], off
	s_waitcnt lgkmcnt(4)
	v_mfma_f32_32x32x16_bf16 v[50:65], v[166:169], v[174:177], v[50:65]
	s_add_u32 m0, vcc_lo, 0x4000
	ds_read_b128 v[206:209], v81 offset:24576
	global_load_lds_dwordx4 v[244:245], off
	s_waitcnt lgkmcnt(4)
	v_mfma_f32_32x32x16_bf16 v[2:17], v[178:181], v[170:173], v[2:17]
	s_add_u32 m0, vcc_lo, 0x10400
	ds_read_b128 v[210:213], v81 offset:26624
	global_load_lds_dwordx4 v[76:77], off
	v_mfma_f32_32x32x16_bf16 v[18:33], v[178:181], v[174:177], v[18:33]
	s_add_u32 m0, vcc_lo, 0x4400
	ds_read_b128 v[222:225], v79 offset:26624
	global_load_lds_dwordx4 v[246:247], off
	s_waitcnt lgkmcnt(5)
	v_mfma_f32_32x32x16_bf16 v[94:109], v[182:185], v[170:173], v[94:109]
	ds_read_b128 v[236:239], v79 offset:32768
	v_lshl_add_u64 v[66:67], v[66:67], 0, v[82:83]
	v_lshl_add_u64 v[68:69], v[68:69], 0, v[82:83]
	v_lshl_add_u64 v[70:71], v[70:71], 0, v[82:83]
	v_lshl_add_u64 v[72:73], v[72:73], 0, v[82:83]
	v_lshl_add_u64 v[74:75], v[74:75], 0, v[82:83]
	v_lshl_add_u64 v[76:77], v[76:77], 0, v[82:83]
	v_lshl_add_u64 v[126:127], v[126:127], 0, v[82:83]
	v_lshl_add_u64 v[128:129], v[128:129], 0, v[82:83]
	v_lshl_add_u64 v[130:131], v[130:131], 0, v[82:83]
	v_lshl_add_u64 v[132:133], v[132:133], 0, v[82:83]
	v_lshl_add_u64 v[244:245], v[244:245], 0, v[82:83]
	v_lshl_add_u64 v[246:247], v[246:247], 0, v[82:83]
	v_mfma_f32_32x32x16_bf16 v[110:125], v[182:185], v[174:177], v[110:125]
	ds_read_b128 v[240:243], v79 offset:34816
	s_waitcnt lgkmcnt(6)
	v_mfma_f32_32x32x16_bf16 v[134:149], v[188:191], v[170:173], v[134:149]
	v_mfma_f32_32x32x16_bf16 v[150:165], v[188:191], v[174:177], v[150:165]
	s_waitcnt vmcnt(0) lgkmcnt(0)
	s_barrier
	v_mfma_f32_32x32x16_bf16 v[34:49], v[192:195], v[206:209], v[34:49]
	ds_read_b128 v[166:169], v78 offset:49152
	v_mfma_f32_32x32x16_bf16 v[50:65], v[192:195], v[210:213], v[50:65]
	ds_read_b128 v[170:173], v80 offset:49152
	v_mfma_f32_32x32x16_bf16 v[2:17], v[222:225], v[206:209], v[2:17]
	ds_read_b128 v[174:177], v80 offset:51200
	v_mfma_f32_32x32x16_bf16 v[18:33], v[222:225], v[210:213], v[18:33]
	ds_read_b128 v[178:181], v78 offset:51200
	v_mfma_f32_32x32x16_bf16 v[94:109], v[236:239], v[206:209], v[94:109]
	ds_read_b128 v[182:185], v78 offset:57344
	v_mfma_f32_32x32x16_bf16 v[110:125], v[236:239], v[210:213], v[110:125]
	ds_read_b128 v[188:191], v78 offset:59392
	v_mfma_f32_32x32x16_bf16 v[134:149], v[240:243], v[206:209], v[134:149]
	v_mfma_f32_32x32x16_bf16 v[150:165], v[240:243], v[210:213], v[150:165]
	s_waitcnt lgkmcnt(4)
	v_mfma_f32_32x32x16_bf16 v[34:49], v[166:169], v[170:173], v[34:49]
	ds_read_b128 v[192:195], v79 offset:49152
	s_waitcnt lgkmcnt(4)
	v_mfma_f32_32x32x16_bf16 v[50:65], v[166:169], v[174:177], v[50:65]
	ds_read_b128 v[206:209], v81 offset:49152
	s_waitcnt lgkmcnt(4)
	v_mfma_f32_32x32x16_bf16 v[2:17], v[178:181], v[170:173], v[2:17]
	ds_read_b128 v[210:213], v81 offset:51200
	v_mfma_f32_32x32x16_bf16 v[18:33], v[178:181], v[174:177], v[18:33]
	ds_read_b128 v[222:225], v79 offset:51200
	s_waitcnt lgkmcnt(5)
	v_mfma_f32_32x32x16_bf16 v[94:109], v[182:185], v[170:173], v[94:109]
	ds_read_b128 v[236:239], v79 offset:57344
	v_mfma_f32_32x32x16_bf16 v[110:125], v[182:185], v[174:177], v[110:125]
	ds_read_b128 v[240:243], v79 offset:59392
	s_waitcnt lgkmcnt(6)
	v_mfma_f32_32x32x16_bf16 v[134:149], v[188:191], v[170:173], v[134:149]
	v_mfma_f32_32x32x16_bf16 v[150:165], v[188:191], v[174:177], v[150:165]
	s_waitcnt vmcnt(0) lgkmcnt(0)
	s_barrier
	v_mfma_f32_32x32x16_bf16 v[34:49], v[192:195], v[206:209], v[34:49]
	s_add_u32 m0, vcc_lo, 0x6000
	ds_read_b128 v[166:169], v78
	global_load_lds_dwordx4 v[66:67], off
	v_mfma_f32_32x32x16_bf16 v[50:65], v[192:195], v[210:213], v[50:65]
	s_add_u32 m0, vcc_lo, 0xc000
	ds_read_b128 v[170:173], v80
	global_load_lds_dwordx4 v[126:127], off
	v_mfma_f32_32x32x16_bf16 v[2:17], v[222:225], v[206:209], v[2:17]
	s_add_u32 m0, vcc_lo, 0x6400
	ds_read_b128 v[174:177], v80 offset:2048
	global_load_lds_dwordx4 v[68:69], off
	v_mfma_f32_32x32x16_bf16 v[18:33], v[222:225], v[210:213], v[18:33]
	s_add_u32 m0, vcc_lo, 0xc400
	ds_read_b128 v[178:181], v78 offset:2048
	global_load_lds_dwordx4 v[128:129], off
	v_mfma_f32_32x32x16_bf16 v[94:109], v[236:239], v[206:209], v[94:109]
	s_add_u32 m0, vcc_lo, 0x8000
	ds_read_b128 v[182:185], v78 offset:8192
	global_load_lds_dwordx4 v[70:71], off
	v_mfma_f32_32x32x16_bf16 v[110:125], v[236:239], v[210:213], v[110:125]
	s_add_u32 m0, vcc_lo, 0xe000
	ds_read_b128 v[188:191], v78 offset:10240
	global_load_lds_dwordx4 v[130:131], off
	v_mfma_f32_32x32x16_bf16 v[134:149], v[240:243], v[206:209], v[134:149]
	s_add_u32 m0, vcc_lo, 0x8400
	s_nop 0
	global_load_lds_dwordx4 v[72:73], off
	v_mfma_f32_32x32x16_bf16 v[150:165], v[240:243], v[210:213], v[150:165]
	s_add_u32 m0, vcc_lo, 0xe400
	s_nop 0
	global_load_lds_dwordx4 v[132:133], off
	s_waitcnt lgkmcnt(4)
	v_mfma_f32_32x32x16_bf16 v[34:49], v[166:169], v[170:173], v[34:49]
	s_add_u32 m0, vcc_lo, 0xa000
	ds_read_b128 v[192:195], v79
	global_load_lds_dwordx4 v[74:75], off
	s_waitcnt lgkmcnt(4)
	v_mfma_f32_32x32x16_bf16 v[50:65], v[166:169], v[174:177], v[50:65]
	s_add_u32 m0, vcc_lo, 0x10000
	ds_read_b128 v[206:209], v81
	global_load_lds_dwordx4 v[244:245], off
	s_waitcnt lgkmcnt(4)
	v_mfma_f32_32x32x16_bf16 v[2:17], v[178:181], v[170:173], v[2:17]
	s_add_u32 m0, vcc_lo, 0xa400
	ds_read_b128 v[210:213], v81 offset:2048
	global_load_lds_dwordx4 v[76:77], off
	v_mfma_f32_32x32x16_bf16 v[18:33], v[178:181], v[174:177], v[18:33]
	s_add_u32 m0, vcc_lo, 0x10400
	ds_read_b128 v[222:225], v79 offset:2048
	global_load_lds_dwordx4 v[246:247], off
	s_waitcnt lgkmcnt(5)
	v_mfma_f32_32x32x16_bf16 v[94:109], v[182:185], v[170:173], v[94:109]
	ds_read_b128 v[236:239], v79 offset:8192
	v_lshl_add_u64 v[66:67], v[66:67], 0, v[82:83]
	v_lshl_add_u64 v[68:69], v[68:69], 0, v[82:83]
	v_lshl_add_u64 v[70:71], v[70:71], 0, v[82:83]
	v_lshl_add_u64 v[72:73], v[72:73], 0, v[82:83]
	v_lshl_add_u64 v[74:75], v[74:75], 0, v[82:83]
	v_lshl_add_u64 v[76:77], v[76:77], 0, v[82:83]
	v_lshl_add_u64 v[126:127], v[126:127], 0, v[82:83]
	v_lshl_add_u64 v[128:129], v[128:129], 0, v[82:83]
	v_lshl_add_u64 v[130:131], v[130:131], 0, v[82:83]
	v_lshl_add_u64 v[132:133], v[132:133], 0, v[82:83]
	v_lshl_add_u64 v[244:245], v[244:245], 0, v[82:83]
	v_lshl_add_u64 v[246:247], v[246:247], 0, v[82:83]
	v_mfma_f32_32x32x16_bf16 v[110:125], v[182:185], v[174:177], v[110:125]
	ds_read_b128 v[240:243], v79 offset:10240
	s_waitcnt lgkmcnt(6)
	v_mfma_f32_32x32x16_bf16 v[134:149], v[188:191], v[170:173], v[134:149]
	v_mfma_f32_32x32x16_bf16 v[150:165], v[188:191], v[174:177], v[150:165]
	s_waitcnt vmcnt(0) lgkmcnt(0)
	s_barrier
	v_mfma_f32_32x32x16_bf16 v[34:49], v[192:195], v[206:209], v[34:49]
	ds_read_b128 v[166:169], v78 offset:24576
	v_mfma_f32_32x32x16_bf16 v[50:65], v[192:195], v[210:213], v[50:65]
	ds_read_b128 v[170:173], v80 offset:24576
	v_mfma_f32_32x32x16_bf16 v[2:17], v[222:225], v[206:209], v[2:17]
	ds_read_b128 v[174:177], v80 offset:26624
	v_mfma_f32_32x32x16_bf16 v[18:33], v[222:225], v[210:213], v[18:33]
	ds_read_b128 v[178:181], v78 offset:26624
	v_mfma_f32_32x32x16_bf16 v[94:109], v[236:239], v[206:209], v[94:109]
	ds_read_b128 v[182:185], v78 offset:32768
	v_mfma_f32_32x32x16_bf16 v[110:125], v[236:239], v[210:213], v[110:125]
	ds_read_b128 v[188:191], v78 offset:34816
	v_mfma_f32_32x32x16_bf16 v[134:149], v[240:243], v[206:209], v[134:149]
	v_mfma_f32_32x32x16_bf16 v[150:165], v[240:243], v[210:213], v[150:165]
	s_waitcnt lgkmcnt(4)
	v_mfma_f32_32x32x16_bf16 v[34:49], v[166:169], v[170:173], v[34:49]
	ds_read_b128 v[192:195], v79 offset:24576
	s_waitcnt lgkmcnt(4)
	v_mfma_f32_32x32x16_bf16 v[50:65], v[166:169], v[174:177], v[50:65]
	ds_read_b128 v[206:209], v81 offset:24576
	s_waitcnt lgkmcnt(4)
	v_mfma_f32_32x32x16_bf16 v[2:17], v[178:181], v[170:173], v[2:17]
	ds_read_b128 v[210:213], v81 offset:26624
	v_mfma_f32_32x32x16_bf16 v[18:33], v[178:181], v[174:177], v[18:33]
	ds_read_b128 v[222:225], v79 offset:26624
	s_waitcnt lgkmcnt(5)
	v_mfma_f32_32x32x16_bf16 v[94:109], v[182:185], v[170:173], v[94:109]
	ds_read_b128 v[236:239], v79 offset:32768
	v_mfma_f32_32x32x16_bf16 v[110:125], v[182:185], v[174:177], v[110:125]
	ds_read_b128 v[240:243], v79 offset:34816
	s_waitcnt lgkmcnt(6)
	v_mfma_f32_32x32x16_bf16 v[134:149], v[188:191], v[170:173], v[134:149]
	v_mfma_f32_32x32x16_bf16 v[150:165], v[188:191], v[174:177], v[150:165]
	s_waitcnt vmcnt(0) lgkmcnt(0)
	s_barrier
	v_mfma_f32_32x32x16_bf16 v[34:49], v[192:195], v[206:209], v[34:49]
	s_mov_b32 m0, vcc_lo
	ds_read_b128 v[166:169], v78 offset:49152
	global_load_lds_dwordx4 v[66:67], off
	v_mfma_f32_32x32x16_bf16 v[50:65], v[192:195], v[210:213], v[50:65]
	s_add_u32 m0, vcc_lo, 0x6000
	ds_read_b128 v[170:173], v80 offset:49152
	global_load_lds_dwordx4 v[126:127], off
	v_mfma_f32_32x32x16_bf16 v[2:17], v[222:225], v[206:209], v[2:17]
	s_add_u32 m0, vcc_lo, 0x400
	ds_read_b128 v[174:177], v80 offset:51200
	global_load_lds_dwordx4 v[68:69], off
	v_mfma_f32_32x32x16_bf16 v[18:33], v[222:225], v[210:213], v[18:33]
	s_add_u32 m0, vcc_lo, 0x6400
	ds_read_b128 v[178:181], v78 offset:51200
	global_load_lds_dwordx4 v[128:129], off
	v_mfma_f32_32x32x16_bf16 v[94:109], v[236:239], v[206:209], v[94:109]
	s_add_u32 m0, vcc_lo, 0x2000
	ds_read_b128 v[182:185], v78 offset:57344
	global_load_lds_dwordx4 v[70:71], off
	v_mfma_f32_32x32x16_bf16 v[110:125], v[236:239], v[210:213], v[110:125]
	s_add_u32 m0, vcc_lo, 0x8000
	ds_read_b128 v[188:191], v78 offset:59392
	global_load_lds_dwordx4 v[130:131], off
	v_mfma_f32_32x32x16_bf16 v[134:149], v[240:243], v[206:209], v[134:149]
	s_add_u32 m0, vcc_lo, 0x2400
	s_nop 0
	global_load_lds_dwordx4 v[72:73], off
	v_mfma_f32_32x32x16_bf16 v[150:165], v[240:243], v[210:213], v[150:165]
	s_add_u32 m0, vcc_lo, 0x8400
	s_nop 0
	global_load_lds_dwordx4 v[132:133], off
	s_waitcnt lgkmcnt(4)
	v_mfma_f32_32x32x16_bf16 v[34:49], v[166:169], v[170:173], v[34:49]
	s_add_u32 m0, vcc_lo, 0x4000
	ds_read_b128 v[192:195], v79 offset:49152
	global_load_lds_dwordx4 v[74:75], off
	s_waitcnt lgkmcnt(4)
	v_mfma_f32_32x32x16_bf16 v[50:65], v[166:169], v[174:177], v[50:65]
	s_add_u32 m0, vcc_lo, 0xa000
	ds_read_b128 v[206:209], v81 offset:49152
	global_load_lds_dwordx4 v[244:245], off
	s_waitcnt lgkmcnt(4)
	v_mfma_f32_32x32x16_bf16 v[2:17], v[178:181], v[170:173], v[2:17]
	s_add_u32 m0, vcc_lo, 0x4400
	ds_read_b128 v[210:213], v81 offset:51200
	global_load_lds_dwordx4 v[76:77], off
	v_mfma_f32_32x32x16_bf16 v[18:33], v[178:181], v[174:177], v[18:33]
	s_add_u32 m0, vcc_lo, 0xa400
	ds_read_b128 v[222:225], v79 offset:51200
	global_load_lds_dwordx4 v[246:247], off
	s_waitcnt lgkmcnt(5)
	v_mfma_f32_32x32x16_bf16 v[94:109], v[182:185], v[170:173], v[94:109]
	ds_read_b128 v[236:239], v79 offset:57344
	v_lshl_add_u64 v[66:67], v[66:67], 0, v[82:83]
	v_lshl_add_u64 v[68:69], v[68:69], 0, v[82:83]
	v_lshl_add_u64 v[70:71], v[70:71], 0, v[82:83]
	v_lshl_add_u64 v[72:73], v[72:73], 0, v[82:83]
	v_lshl_add_u64 v[74:75], v[74:75], 0, v[82:83]
	v_lshl_add_u64 v[76:77], v[76:77], 0, v[82:83]
	v_lshl_add_u64 v[126:127], v[126:127], 0, v[82:83]
	v_lshl_add_u64 v[128:129], v[128:129], 0, v[82:83]
	v_lshl_add_u64 v[130:131], v[130:131], 0, v[82:83]
	v_lshl_add_u64 v[132:133], v[132:133], 0, v[82:83]
	v_lshl_add_u64 v[244:245], v[244:245], 0, v[82:83]
	v_lshl_add_u64 v[246:247], v[246:247], 0, v[82:83]
	v_mfma_f32_32x32x16_bf16 v[110:125], v[182:185], v[174:177], v[110:125]
	ds_read_b128 v[240:243], v79 offset:59392
	s_waitcnt lgkmcnt(6)
	v_mfma_f32_32x32x16_bf16 v[134:149], v[188:191], v[170:173], v[134:149]
	v_mfma_f32_32x32x16_bf16 v[150:165], v[188:191], v[174:177], v[150:165]
	s_waitcnt vmcnt(0) lgkmcnt(0)
	s_barrier
	v_mfma_f32_32x32x16_bf16 v[34:49], v[192:195], v[206:209], v[34:49]
	ds_read_b128 v[166:169], v78
	v_mfma_f32_32x32x16_bf16 v[50:65], v[192:195], v[210:213], v[50:65]
	ds_read_b128 v[170:173], v80
	v_mfma_f32_32x32x16_bf16 v[2:17], v[222:225], v[206:209], v[2:17]
	ds_read_b128 v[174:177], v80 offset:2048
	v_mfma_f32_32x32x16_bf16 v[18:33], v[222:225], v[210:213], v[18:33]
	ds_read_b128 v[178:181], v78 offset:2048
	v_mfma_f32_32x32x16_bf16 v[94:109], v[236:239], v[206:209], v[94:109]
	ds_read_b128 v[182:185], v78 offset:8192
	v_mfma_f32_32x32x16_bf16 v[110:125], v[236:239], v[210:213], v[110:125]
	ds_read_b128 v[188:191], v78 offset:10240
	v_mfma_f32_32x32x16_bf16 v[134:149], v[240:243], v[206:209], v[134:149]
	v_mfma_f32_32x32x16_bf16 v[150:165], v[240:243], v[210:213], v[150:165]
	s_waitcnt lgkmcnt(4)
	v_mfma_f32_32x32x16_bf16 v[34:49], v[166:169], v[170:173], v[34:49]
	ds_read_b128 v[192:195], v79
	s_waitcnt lgkmcnt(4)
	v_mfma_f32_32x32x16_bf16 v[50:65], v[166:169], v[174:177], v[50:65]
	ds_read_b128 v[206:209], v81
	s_waitcnt lgkmcnt(4)
	v_mfma_f32_32x32x16_bf16 v[2:17], v[178:181], v[170:173], v[2:17]
	ds_read_b128 v[210:213], v81 offset:2048
	v_mfma_f32_32x32x16_bf16 v[18:33], v[178:181], v[174:177], v[18:33]
	ds_read_b128 v[222:225], v79 offset:2048
	s_waitcnt lgkmcnt(5)
	v_mfma_f32_32x32x16_bf16 v[94:109], v[182:185], v[170:173], v[94:109]
	ds_read_b128 v[236:239], v79 offset:8192
	v_mfma_f32_32x32x16_bf16 v[110:125], v[182:185], v[174:177], v[110:125]
	ds_read_b128 v[240:243], v79 offset:10240
	s_waitcnt lgkmcnt(6)
	v_mfma_f32_32x32x16_bf16 v[134:149], v[188:191], v[170:173], v[134:149]
	v_mfma_f32_32x32x16_bf16 v[150:165], v[188:191], v[174:177], v[150:165]
	s_waitcnt vmcnt(0) lgkmcnt(0)
	s_barrier
	s_sub_u32 vcc_hi, vcc_hi, 1
	s_cmp_lg_u32 vcc_hi, 0
	s_cbranch_scc1 .Lg_ffninp_loop
	v_mfma_f32_32x32x16_bf16 v[34:49], v[192:195], v[206:209], v[34:49]
	s_add_u32 m0, vcc_lo, 0xc000
	ds_read_b128 v[166:169], v78 offset:24576
	global_load_lds_dwordx4 v[66:67], off
	v_mfma_f32_32x32x16_bf16 v[50:65], v[192:195], v[210:213], v[50:65]
	s_mov_b32 m0, vcc_lo
	ds_read_b128 v[170:173], v80 offset:24576
	global_load_lds_dwordx4 v[126:127], off
	v_mfma_f32_32x32x16_bf16 v[2:17], v[222:225], v[206:209], v[2:17]
	s_add_u32 m0, vcc_lo, 0xc400
	ds_read_b128 v[174:177], v80 offset:26624
	global_load_lds_dwordx4 v[68:69], off
	v_mfma_f32_32x32x16_bf16 v[18:33], v[222:225], v[210:213], v[18:33]
	s_add_u32 m0, vcc_lo, 0x400
	ds_read_b128 v[178:181], v78 offset:26624
	global_load_lds_dwordx4 v[128:129], off
	v_mfma_f32_32x32x16_bf16 v[94:109], v[236:239], v[206:209], v[94:109]
	s_add_u32 m0, vcc_lo, 0xe000
	ds_read_b128 v[182:185], v78 offset:32768
	global_load_lds_dwordx4 v[70:71], off
	v_mfma_f32_32x32x16_bf16 v[110:125], v[236:239], v[210:213], v[110:125]
	s_add_u32 m0, vcc_lo, 0x2000
	ds_read_b128 v[188:191], v78 offset:34816
	global_load_lds_dwordx4 v[130:131], off
	v_mfma_f32_32x32x16_bf16 v[134:149], v[240:243], v[206:209], v[134:149]
	s_add_u32 m0, vcc_lo, 0xe400
	s_nop 0
	global_load_lds_dwordx4 v[72:73], off
	v_mfma_f32_32x32x16_bf16 v[150:165], v[240:243], v[210:213], v[150:165]
	s_add_u32 m0, vcc_lo, 0x2400
	s_nop 0
	global_load_lds_dwordx4 v[132:133], off
	s_waitcnt lgkmcnt(4)
	v_mfma_f32_32x32x16_bf16 v[34:49], v[166:169], v[170:173], v[34:49]
	s_add_u32 m0, vcc_lo, 0x10000
	ds_read_b128 v[192:195], v79 offset:24576
	global_load_lds_dwordx4 v[74:75], off
	s_waitcnt lgkmcnt(4)
	v_mfma_f32_32x32x16_bf16 v[50:65], v[166:169], v[174:177], v[50:65]
	s_add_u32 m0, vcc_lo, 0x4000
	ds_read_b128 v[206:209], v81 offset:24576
	global_load_lds_dwordx4 v[244:245], off
	s_waitcnt lgkmcnt(4)
	v_mfma_f32_32x32x16_bf16 v[2:17], v[178:181], v[170:173], v[2:17]
	s_add_u32 m0, vcc_lo, 0x10400
	ds_read_b128 v[210:213], v81 offset:26624
	global_load_lds_dwordx4 v[76:77], off
	v_mfma_f32_32x32x16_bf16 v[18:33], v[178:181], v[174:177], v[18:33]
	s_add_u32 m0, vcc_lo, 0x4400
	ds_read_b128 v[222:225], v79 offset:26624
	global_load_lds_dwordx4 v[246:247], off
	s_waitcnt lgkmcnt(5)
	v_mfma_f32_32x32x16_bf16 v[94:109], v[182:185], v[170:173], v[94:109]
	ds_read_b128 v[236:239], v79 offset:32768
	v_lshl_add_u64 v[66:67], v[66:67], 0, v[82:83]
	v_lshl_add_u64 v[68:69], v[68:69], 0, v[82:83]
	v_lshl_add_u64 v[70:71], v[70:71], 0, v[82:83]
	v_lshl_add_u64 v[72:73], v[72:73], 0, v[82:83]
	v_lshl_add_u64 v[74:75], v[74:75], 0, v[82:83]
	v_lshl_add_u64 v[76:77], v[76:77], 0, v[82:83]
	v_lshl_add_u64 v[126:127], v[126:127], 0, v[82:83]
	v_lshl_add_u64 v[128:129], v[128:129], 0, v[82:83]
	v_lshl_add_u64 v[130:131], v[130:131], 0, v[82:83]
	v_lshl_add_u64 v[132:133], v[132:133], 0, v[82:83]
	v_lshl_add_u64 v[244:245], v[244:245], 0, v[82:83]
	v_lshl_add_u64 v[246:247], v[246:247], 0, v[82:83]
	v_mfma_f32_32x32x16_bf16 v[110:125], v[182:185], v[174:177], v[110:125]
	ds_read_b128 v[240:243], v79 offset:34816
	s_waitcnt lgkmcnt(6)
	v_mfma_f32_32x32x16_bf16 v[134:149], v[188:191], v[170:173], v[134:149]
	v_mfma_f32_32x32x16_bf16 v[150:165], v[188:191], v[174:177], v[150:165]
	s_waitcnt vmcnt(0) lgkmcnt(0)
	s_barrier
	v_mfma_f32_32x32x16_bf16 v[34:49], v[192:195], v[206:209], v[34:49]
	ds_read_b128 v[166:169], v78 offset:49152
	v_mfma_f32_32x32x16_bf16 v[50:65], v[192:195], v[210:213], v[50:65]
	ds_read_b128 v[170:173], v80 offset:49152
	v_mfma_f32_32x32x16_bf16 v[2:17], v[222:225], v[206:209], v[2:17]
	ds_read_b128 v[174:177], v80 offset:51200
	v_mfma_f32_32x32x16_bf16 v[18:33], v[222:225], v[210:213], v[18:33]
	ds_read_b128 v[178:181], v78 offset:51200
	v_mfma_f32_32x32x16_bf16 v[94:109], v[236:239], v[206:209], v[94:109]
	ds_read_b128 v[182:185], v78 offset:57344
	v_mfma_f32_32x32x16_bf16 v[110:125], v[236:239], v[210:213], v[110:125]
	ds_read_b128 v[188:191], v78 offset:59392
	v_mfma_f32_32x32x16_bf16 v[134:149], v[240:243], v[206:209], v[134:149]
	v_mfma_f32_32x32x16_bf16 v[150:165], v[240:243], v[210:213], v[150:165]
	s_waitcnt lgkmcnt(4)
	v_mfma_f32_32x32x16_bf16 v[34:49], v[166:169], v[170:173], v[34:49]
	ds_read_b128 v[192:195], v79 offset:49152
	s_waitcnt lgkmcnt(4)
	v_mfma_f32_32x32x16_bf16 v[50:65], v[166:169], v[174:177], v[50:65]
	ds_read_b128 v[206:209], v81 offset:49152
	s_waitcnt lgkmcnt(4)
	v_mfma_f32_32x32x16_bf16 v[2:17], v[178:181], v[170:173], v[2:17]
	ds_read_b128 v[210:213], v81 offset:51200
	v_mfma_f32_32x32x16_bf16 v[18:33], v[178:181], v[174:177], v[18:33]
	ds_read_b128 v[222:225], v79 offset:51200
	s_waitcnt lgkmcnt(5)
	v_mfma_f32_32x32x16_bf16 v[94:109], v[182:185], v[170:173], v[94:109]
	ds_read_b128 v[236:239], v79 offset:57344
	v_mfma_f32_32x32x16_bf16 v[110:125], v[182:185], v[174:177], v[110:125]
	ds_read_b128 v[240:243], v79 offset:59392
	s_waitcnt lgkmcnt(6)
	v_mfma_f32_32x32x16_bf16 v[134:149], v[188:191], v[170:173], v[134:149]
	v_mfma_f32_32x32x16_bf16 v[150:165], v[188:191], v[174:177], v[150:165]
	s_waitcnt vmcnt(0) lgkmcnt(0)
	s_barrier
	v_mfma_f32_32x32x16_bf16 v[34:49], v[192:195], v[206:209], v[34:49]
	s_add_u32 m0, vcc_lo, 0x6000
	ds_read_b128 v[166:169], v78
	global_load_lds_dwordx4 v[66:67], off
	v_mfma_f32_32x32x16_bf16 v[50:65], v[192:195], v[210:213], v[50:65]
	s_add_u32 m0, vcc_lo, 0xc000
	ds_read_b128 v[170:173], v80
	global_load_lds_dwordx4 v[126:127], off
	v_mfma_f32_32x32x16_bf16 v[2:17], v[222:225], v[206:209], v[2:17]
	s_add_u32 m0, vcc_lo, 0x6400
	ds_read_b128 v[174:177], v80 offset:2048
	global_load_lds_dwordx4 v[68:69], off
	v_mfma_f32_32x32x16_bf16 v[18:33], v[222:225], v[210:213], v[18:33]
	s_add_u32 m0, vcc_lo, 0xc400
	ds_read_b128 v[178:181], v78 offset:2048
	global_load_lds_dwordx4 v[128:129], off
	v_mfma_f32_32x32x16_bf16 v[94:109], v[236:239], v[206:209], v[94:109]
	s_add_u32 m0, vcc_lo, 0x8000
	ds_read_b128 v[182:185], v78 offset:8192
	global_load_lds_dwordx4 v[70:71], off
	v_mfma_f32_32x32x16_bf16 v[110:125], v[236:239], v[210:213], v[110:125]
	s_add_u32 m0, vcc_lo, 0xe000
	ds_read_b128 v[188:191], v78 offset:10240
	global_load_lds_dwordx4 v[130:131], off
	v_mfma_f32_32x32x16_bf16 v[134:149], v[240:243], v[206:209], v[134:149]
	s_add_u32 m0, vcc_lo, 0x8400
	s_nop 0
	global_load_lds_dwordx4 v[72:73], off
	v_mfma_f32_32x32x16_bf16 v[150:165], v[240:243], v[210:213], v[150:165]
	s_add_u32 m0, vcc_lo, 0xe400
	s_nop 0
	global_load_lds_dwordx4 v[132:133], off
	s_waitcnt lgkmcnt(4)
	v_mfma_f32_32x32x16_bf16 v[34:49], v[166:169], v[170:173], v[34:49]
	s_add_u32 m0, vcc_lo, 0xa000
	ds_read_b128 v[192:195], v79
	global_load_lds_dwordx4 v[74:75], off
	s_waitcnt lgkmcnt(4)
	v_mfma_f32_32x32x16_bf16 v[50:65], v[166:169], v[174:177], v[50:65]
	s_add_u32 m0, vcc_lo, 0x10000
	ds_read_b128 v[206:209], v81
	global_load_lds_dwordx4 v[244:245], off
	s_waitcnt lgkmcnt(4)
	v_mfma_f32_32x32x16_bf16 v[2:17], v[178:181], v[170:173], v[2:17]
	s_add_u32 m0, vcc_lo, 0xa400
	ds_read_b128 v[210:213], v81 offset:2048
	global_load_lds_dwordx4 v[76:77], off
	v_mfma_f32_32x32x16_bf16 v[18:33], v[178:181], v[174:177], v[18:33]
	s_add_u32 m0, vcc_lo, 0x10400
	ds_read_b128 v[222:225], v79 offset:2048
	global_load_lds_dwordx4 v[246:247], off
	s_waitcnt lgkmcnt(5)
	v_mfma_f32_32x32x16_bf16 v[94:109], v[182:185], v[170:173], v[94:109]
	ds_read_b128 v[236:239], v79 offset:8192
	v_lshl_add_u64 v[66:67], v[66:67], 0, v[82:83]
	v_lshl_add_u64 v[68:69], v[68:69], 0, v[82:83]
	v_lshl_add_u64 v[70:71], v[70:71], 0, v[82:83]
	v_lshl_add_u64 v[72:73], v[72:73], 0, v[82:83]
	v_lshl_add_u64 v[74:75], v[74:75], 0, v[82:83]
	v_lshl_add_u64 v[76:77], v[76:77], 0, v[82:83]
	v_lshl_add_u64 v[126:127], v[126:127], 0, v[82:83]
	v_lshl_add_u64 v[128:129], v[128:129], 0, v[82:83]
	v_lshl_add_u64 v[130:131], v[130:131], 0, v[82:83]
	v_lshl_add_u64 v[132:133], v[132:133], 0, v[82:83]
	v_lshl_add_u64 v[244:245], v[244:245], 0, v[82:83]
	v_lshl_add_u64 v[246:247], v[246:247], 0, v[82:83]
	v_mfma_f32_32x32x16_bf16 v[110:125], v[182:185], v[174:177], v[110:125]
	ds_read_b128 v[240:243], v79 offset:10240
	s_waitcnt lgkmcnt(6)
	v_mfma_f32_32x32x16_bf16 v[134:149], v[188:191], v[170:173], v[134:149]
	v_mfma_f32_32x32x16_bf16 v[150:165], v[188:191], v[174:177], v[150:165]
	s_waitcnt vmcnt(0) lgkmcnt(0)
	s_barrier
	v_mfma_f32_32x32x16_bf16 v[34:49], v[192:195], v[206:209], v[34:49]
	ds_read_b128 v[166:169], v78 offset:24576
	v_mfma_f32_32x32x16_bf16 v[50:65], v[192:195], v[210:213], v[50:65]
	ds_read_b128 v[170:173], v80 offset:24576
	v_mfma_f32_32x32x16_bf16 v[2:17], v[222:225], v[206:209], v[2:17]
	ds_read_b128 v[174:177], v80 offset:26624
	v_mfma_f32_32x32x16_bf16 v[18:33], v[222:225], v[210:213], v[18:33]
	ds_read_b128 v[178:181], v78 offset:26624
	v_mfma_f32_32x32x16_bf16 v[94:109], v[236:239], v[206:209], v[94:109]
	ds_read_b128 v[182:185], v78 offset:32768
	v_mfma_f32_32x32x16_bf16 v[110:125], v[236:239], v[210:213], v[110:125]
	ds_read_b128 v[188:191], v78 offset:34816
	v_mfma_f32_32x32x16_bf16 v[134:149], v[240:243], v[206:209], v[134:149]
	v_mfma_f32_32x32x16_bf16 v[150:165], v[240:243], v[210:213], v[150:165]
	s_waitcnt lgkmcnt(4)
	v_mfma_f32_32x32x16_bf16 v[34:49], v[166:169], v[170:173], v[34:49]
	ds_read_b128 v[192:195], v79 offset:24576
	s_waitcnt lgkmcnt(4)
	v_mfma_f32_32x32x16_bf16 v[50:65], v[166:169], v[174:177], v[50:65]
	ds_read_b128 v[206:209], v81 offset:24576
	s_waitcnt lgkmcnt(4)
	v_mfma_f32_32x32x16_bf16 v[2:17], v[178:181], v[170:173], v[2:17]
	ds_read_b128 v[210:213], v81 offset:26624
	v_mfma_f32_32x32x16_bf16 v[18:33], v[178:181], v[174:177], v[18:33]
	ds_read_b128 v[222:225], v79 offset:26624
	s_waitcnt lgkmcnt(5)
	v_mfma_f32_32x32x16_bf16 v[94:109], v[182:185], v[170:173], v[94:109]
	ds_read_b128 v[236:239], v79 offset:32768
	v_mfma_f32_32x32x16_bf16 v[110:125], v[182:185], v[174:177], v[110:125]
	ds_read_b128 v[240:243], v79 offset:34816
	s_waitcnt lgkmcnt(6)
	v_mfma_f32_32x32x16_bf16 v[134:149], v[188:191], v[170:173], v[134:149]
	v_mfma_f32_32x32x16_bf16 v[150:165], v[188:191], v[174:177], v[150:165]
	s_waitcnt vmcnt(0) lgkmcnt(0)
	s_barrier
	v_mfma_f32_32x32x16_bf16 v[34:49], v[192:195], v[206:209], v[34:49]
	s_mov_b32 m0, vcc_lo
	ds_read_b128 v[166:169], v78 offset:49152
	global_load_lds_dwordx4 v[66:67], off
	v_mfma_f32_32x32x16_bf16 v[50:65], v[192:195], v[210:213], v[50:65]
	s_add_u32 m0, vcc_lo, 0x6000
	ds_read_b128 v[170:173], v80 offset:49152
	global_load_lds_dwordx4 v[126:127], off
	v_mfma_f32_32x32x16_bf16 v[2:17], v[222:225], v[206:209], v[2:17]
	s_add_u32 m0, vcc_lo, 0x400
	ds_read_b128 v[174:177], v80 offset:51200
	global_load_lds_dwordx4 v[68:69], off
	v_mfma_f32_32x32x16_bf16 v[18:33], v[222:225], v[210:213], v[18:33]
	s_add_u32 m0, vcc_lo, 0x6400
	ds_read_b128 v[178:181], v78 offset:51200
	global_load_lds_dwordx4 v[128:129], off
	v_mfma_f32_32x32x16_bf16 v[94:109], v[236:239], v[206:209], v[94:109]
	s_add_u32 m0, vcc_lo, 0x2000
	ds_read_b128 v[182:185], v78 offset:57344
	global_load_lds_dwordx4 v[70:71], off
	v_mfma_f32_32x32x16_bf16 v[110:125], v[236:239], v[210:213], v[110:125]
	s_add_u32 m0, vcc_lo, 0x8000
	ds_read_b128 v[188:191], v78 offset:59392
	global_load_lds_dwordx4 v[130:131], off
	v_mfma_f32_32x32x16_bf16 v[134:149], v[240:243], v[206:209], v[134:149]
	s_add_u32 m0, vcc_lo, 0x2400
	s_nop 0
	global_load_lds_dwordx4 v[72:73], off
	v_mfma_f32_32x32x16_bf16 v[150:165], v[240:243], v[210:213], v[150:165]
	s_add_u32 m0, vcc_lo, 0x8400
	s_nop 0
	global_load_lds_dwordx4 v[132:133], off
	s_waitcnt lgkmcnt(4)
	v_mfma_f32_32x32x16_bf16 v[34:49], v[166:169], v[170:173], v[34:49]
	s_add_u32 m0, vcc_lo, 0x4000
	ds_read_b128 v[192:195], v79 offset:49152
	global_load_lds_dwordx4 v[74:75], off
	s_waitcnt lgkmcnt(4)
	v_mfma_f32_32x32x16_bf16 v[50:65], v[166:169], v[174:177], v[50:65]
	s_add_u32 m0, vcc_lo, 0xa000
	ds_read_b128 v[206:209], v81 offset:49152
	global_load_lds_dwordx4 v[244:245], off
	s_waitcnt lgkmcnt(4)
	v_mfma_f32_32x32x16_bf16 v[2:17], v[178:181], v[170:173], v[2:17]
	s_add_u32 m0, vcc_lo, 0x4400
	ds_read_b128 v[210:213], v81 offset:51200
	global_load_lds_dwordx4 v[76:77], off
	v_mfma_f32_32x32x16_bf16 v[18:33], v[178:181], v[174:177], v[18:33]
	s_add_u32 m0, vcc_lo, 0xa400
	ds_read_b128 v[222:225], v79 offset:51200
	global_load_lds_dwordx4 v[246:247], off
	s_waitcnt lgkmcnt(5)
	v_mfma_f32_32x32x16_bf16 v[94:109], v[182:185], v[170:173], v[94:109]
	ds_read_b128 v[236:239], v79 offset:57344
	v_lshl_add_u64 v[66:67], v[66:67], 0, v[82:83]
	v_lshl_add_u64 v[68:69], v[68:69], 0, v[82:83]
	v_lshl_add_u64 v[70:71], v[70:71], 0, v[82:83]
	v_lshl_add_u64 v[72:73], v[72:73], 0, v[82:83]
	v_lshl_add_u64 v[74:75], v[74:75], 0, v[82:83]
	v_lshl_add_u64 v[76:77], v[76:77], 0, v[82:83]
	v_lshl_add_u64 v[126:127], v[126:127], 0, v[82:83]
	v_lshl_add_u64 v[128:129], v[128:129], 0, v[82:83]
	v_lshl_add_u64 v[130:131], v[130:131], 0, v[82:83]
	v_lshl_add_u64 v[132:133], v[132:133], 0, v[82:83]
	v_lshl_add_u64 v[244:245], v[244:245], 0, v[82:83]
	v_lshl_add_u64 v[246:247], v[246:247], 0, v[82:83]
	v_mfma_f32_32x32x16_bf16 v[110:125], v[182:185], v[174:177], v[110:125]
	ds_read_b128 v[240:243], v79 offset:59392
	s_waitcnt lgkmcnt(6)
	v_mfma_f32_32x32x16_bf16 v[134:149], v[188:191], v[170:173], v[134:149]
	v_mfma_f32_32x32x16_bf16 v[150:165], v[188:191], v[174:177], v[150:165]
	s_waitcnt vmcnt(0) lgkmcnt(0)
	s_barrier
	v_mfma_f32_32x32x16_bf16 v[34:49], v[192:195], v[206:209], v[34:49]
	ds_read_b128 v[166:169], v78
	v_mfma_f32_32x32x16_bf16 v[50:65], v[192:195], v[210:213], v[50:65]
	ds_read_b128 v[170:173], v80
	v_mfma_f32_32x32x16_bf16 v[2:17], v[222:225], v[206:209], v[2:17]
	ds_read_b128 v[174:177], v80 offset:2048
	v_mfma_f32_32x32x16_bf16 v[18:33], v[222:225], v[210:213], v[18:33]
	ds_read_b128 v[178:181], v78 offset:2048
	v_mfma_f32_32x32x16_bf16 v[94:109], v[236:239], v[206:209], v[94:109]
	ds_read_b128 v[182:185], v78 offset:8192
	v_mfma_f32_32x32x16_bf16 v[110:125], v[236:239], v[210:213], v[110:125]
	ds_read_b128 v[188:191], v78 offset:10240
	v_mfma_f32_32x32x16_bf16 v[134:149], v[240:243], v[206:209], v[134:149]
	v_mfma_f32_32x32x16_bf16 v[150:165], v[240:243], v[210:213], v[150:165]
	s_waitcnt lgkmcnt(4)
	v_mfma_f32_32x32x16_bf16 v[34:49], v[166:169], v[170:173], v[34:49]
	ds_read_b128 v[192:195], v79
	s_waitcnt lgkmcnt(4)
	v_mfma_f32_32x32x16_bf16 v[50:65], v[166:169], v[174:177], v[50:65]
	ds_read_b128 v[206:209], v81
	s_waitcnt lgkmcnt(4)
	v_mfma_f32_32x32x16_bf16 v[2:17], v[178:181], v[170:173], v[2:17]
	ds_read_b128 v[210:213], v81 offset:2048
	v_mfma_f32_32x32x16_bf16 v[18:33], v[178:181], v[174:177], v[18:33]
	ds_read_b128 v[222:225], v79 offset:2048
	s_waitcnt lgkmcnt(5)
	v_mfma_f32_32x32x16_bf16 v[94:109], v[182:185], v[170:173], v[94:109]
	ds_read_b128 v[236:239], v79 offset:8192
	v_mfma_f32_32x32x16_bf16 v[110:125], v[182:185], v[174:177], v[110:125]
	ds_read_b128 v[240:243], v79 offset:10240
	s_waitcnt lgkmcnt(6)
	v_mfma_f32_32x32x16_bf16 v[134:149], v[188:191], v[170:173], v[134:149]
	v_mfma_f32_32x32x16_bf16 v[150:165], v[188:191], v[174:177], v[150:165]
	s_waitcnt vmcnt(0) lgkmcnt(0)
	s_barrier
	v_mfma_f32_32x32x16_bf16 v[34:49], v[192:195], v[206:209], v[34:49]
	ds_read_b128 v[166:169], v78 offset:24576
	v_mfma_f32_32x32x16_bf16 v[50:65], v[192:195], v[210:213], v[50:65]
	ds_read_b128 v[170:173], v80 offset:24576
	v_mfma_f32_32x32x16_bf16 v[2:17], v[222:225], v[206:209], v[2:17]
	ds_read_b128 v[174:177], v80 offset:26624
	v_mfma_f32_32x32x16_bf16 v[18:33], v[222:225], v[210:213], v[18:33]
	ds_read_b128 v[178:181], v78 offset:26624
	v_mfma_f32_32x32x16_bf16 v[94:109], v[236:239], v[206:209], v[94:109]
	ds_read_b128 v[182:185], v78 offset:32768
	v_mfma_f32_32x32x16_bf16 v[110:125], v[236:239], v[210:213], v[110:125]
	ds_read_b128 v[188:191], v78 offset:34816
	v_mfma_f32_32x32x16_bf16 v[134:149], v[240:243], v[206:209], v[134:149]
	v_mfma_f32_32x32x16_bf16 v[150:165], v[240:243], v[210:213], v[150:165]
	s_waitcnt lgkmcnt(4)
	v_mfma_f32_32x32x16_bf16 v[34:49], v[166:169], v[170:173], v[34:49]
	ds_read_b128 v[192:195], v79 offset:24576
	s_waitcnt lgkmcnt(4)
	v_mfma_f32_32x32x16_bf16 v[50:65], v[166:169], v[174:177], v[50:65]
	ds_read_b128 v[206:209], v81 offset:24576
	s_waitcnt lgkmcnt(4)
	v_mfma_f32_32x32x16_bf16 v[2:17], v[178:181], v[170:173], v[2:17]
	ds_read_b128 v[210:213], v81 offset:26624
	v_mfma_f32_32x32x16_bf16 v[18:33], v[178:181], v[174:177], v[18:33]
	ds_read_b128 v[222:225], v79 offset:26624
	s_waitcnt lgkmcnt(5)
	v_mfma_f32_32x32x16_bf16 v[94:109], v[182:185], v[170:173], v[94:109]
	ds_read_b128 v[236:239], v79 offset:32768
	v_mfma_f32_32x32x16_bf16 v[110:125], v[182:185], v[174:177], v[110:125]
	ds_read_b128 v[240:243], v79 offset:34816
	s_waitcnt lgkmcnt(6)
	v_mfma_f32_32x32x16_bf16 v[134:149], v[188:191], v[170:173], v[134:149]
	v_mfma_f32_32x32x16_bf16 v[150:165], v[188:191], v[174:177], v[150:165]
	s_waitcnt lgkmcnt(4)
	v_mfma_f32_32x32x16_bf16 v[34:49], v[192:195], v[206:209], v[34:49]
	s_waitcnt lgkmcnt(3)
	v_mfma_f32_32x32x16_bf16 v[50:65], v[192:195], v[210:213], v[50:65]
	s_waitcnt lgkmcnt(2)
	v_mfma_f32_32x32x16_bf16 v[2:17], v[222:225], v[206:209], v[2:17]
	v_mfma_f32_32x32x16_bf16 v[18:33], v[222:225], v[210:213], v[18:33]
	s_waitcnt lgkmcnt(1)
	v_mfma_f32_32x32x16_bf16 v[94:109], v[236:239], v[206:209], v[94:109]
	v_mfma_f32_32x32x16_bf16 v[110:125], v[236:239], v[210:213], v[110:125]
	s_waitcnt lgkmcnt(0)
	v_mfma_f32_32x32x16_bf16 v[134:149], v[240:243], v[206:209], v[134:149]
	v_mfma_f32_32x32x16_bf16 v[150:165], v[240:243], v[210:213], v[150:165]
	s_nop 7
	s_nop 7
	s_mov_b32 m0, 0x7ead
.Lffp_epi:
	v_mul_f32_e32 v67, 0xbfb8aa3b, v34
	v_exp_f32_e32 v67, v67
	v_lshrrev_b32_e32 v66, 3, v90
	v_lshlrev_b32_e32 v0, 1, v0
	v_and_or_b32 v66, v66, 4, v91
	v_add_f32_e32 v67, 1.0, v67
	v_rcp_f32_e32 v67, v67
	v_and_or_b32 v0, v90, 64, v0
	s_barrier
	v_mul_f32_e32 v34, v34, v67
	v_mad_u64_u32 v[66:67], s[24:25], v66, s28, v[0:1]
	v_mul_f32_e32 v0, 0xbfb8aa3b, v35
	v_exp_f32_e32 v0, v0
	v_mul_f32_e32 v34, v50, v34
	v_cvt_pk_bf16_f32 v34, v34, s0
	v_add_f32_e32 v0, 1.0, v0
	v_rcp_f32_e32 v0, v0
	ds_write_b16 v66, v34
	s_mul_i32 s23, s23, 0x57500
	s_nop 0
	v_mul_f32_e32 v0, v35, v0
	v_mul_f32_e32 v0, v51, v0
	v_cvt_pk_bf16_f32 v0, v0, s0
	ds_write_b16 v66, v0 offset:144
	v_mul_f32_e32 v0, 0xbfb8aa3b, v36
	v_exp_f32_e32 v0, v0
	s_nop 0
	v_add_f32_e32 v0, 1.0, v0
	v_rcp_f32_e32 v0, v0
	s_nop 0
	v_mul_f32_e32 v0, v36, v0
	v_mul_f32_e32 v0, v52, v0
	v_cvt_pk_bf16_f32 v0, v0, s0
	ds_write_b16 v66, v0 offset:288
	v_mul_f32_e32 v0, 0xbfb8aa3b, v37
	v_exp_f32_e32 v0, v0
	s_nop 0
	v_add_f32_e32 v0, 1.0, v0
	v_rcp_f32_e32 v0, v0
	s_nop 0
	v_mul_f32_e32 v0, v37, v0
	v_mul_f32_e32 v0, v53, v0
	v_cvt_pk_bf16_f32 v0, v0, s0
	ds_write_b16 v66, v0 offset:432
	v_mul_f32_e32 v0, 0xbfb8aa3b, v38
	v_exp_f32_e32 v0, v0
	s_nop 0
	v_add_f32_e32 v0, 1.0, v0
	v_rcp_f32_e32 v0, v0
	s_nop 0
	v_mul_f32_e32 v0, v38, v0
	v_mul_f32_e32 v0, v54, v0
	v_cvt_pk_bf16_f32 v0, v0, s0
	ds_write_b16 v66, v0 offset:1152
	v_mul_f32_e32 v0, 0xbfb8aa3b, v39
	v_exp_f32_e32 v0, v0
	s_nop 0
	v_add_f32_e32 v0, 1.0, v0
	v_rcp_f32_e32 v0, v0
	s_nop 0
	v_mul_f32_e32 v0, v39, v0
	v_mul_f32_e32 v0, v55, v0
	v_cvt_pk_bf16_f32 v0, v0, s0
	ds_write_b16 v66, v0 offset:1296
	v_mul_f32_e32 v0, 0xbfb8aa3b, v40
	v_exp_f32_e32 v0, v0
	s_nop 0
	v_add_f32_e32 v0, 1.0, v0
	v_rcp_f32_e32 v0, v0
	s_nop 0
	v_mul_f32_e32 v0, v40, v0
	v_mul_f32_e32 v0, v56, v0
	v_cvt_pk_bf16_f32 v0, v0, s0
	ds_write_b16 v66, v0 offset:1440
	v_mul_f32_e32 v0, 0xbfb8aa3b, v41
	v_exp_f32_e32 v0, v0
	s_nop 0
	v_add_f32_e32 v0, 1.0, v0
	v_rcp_f32_e32 v0, v0
	s_nop 0
	v_mul_f32_e32 v0, v41, v0
	v_mul_f32_e32 v0, v57, v0
	v_cvt_pk_bf16_f32 v0, v0, s0
	ds_write_b16 v66, v0 offset:1584
	v_mul_f32_e32 v0, 0xbfb8aa3b, v42
	v_exp_f32_e32 v0, v0
	s_nop 0
	v_add_f32_e32 v0, 1.0, v0
	v_rcp_f32_e32 v0, v0
	s_nop 0
	v_mul_f32_e32 v0, v42, v0
	v_mul_f32_e32 v0, v58, v0
	v_cvt_pk_bf16_f32 v0, v0, s0
	ds_write_b16 v66, v0 offset:2304
	v_mul_f32_e32 v0, 0xbfb8aa3b, v43
	v_exp_f32_e32 v0, v0
	s_nop 0
	v_add_f32_e32 v0, 1.0, v0
	v_rcp_f32_e32 v0, v0
	s_nop 0
	v_mul_f32_e32 v0, v43, v0
	v_mul_f32_e32 v0, v59, v0
	v_cvt_pk_bf16_f32 v0, v0, s0
	ds_write_b16 v66, v0 offset:2448
	v_mul_f32_e32 v0, 0xbfb8aa3b, v44
	v_exp_f32_e32 v0, v0
	s_nop 0
	v_add_f32_e32 v0, 1.0, v0
	v_rcp_f32_e32 v0, v0
	s_nop 0
	v_mul_f32_e32 v0, v44, v0
	v_mul_f32_e32 v0, v60, v0
	v_cvt_pk_bf16_f32 v0, v0, s0
	ds_write_b16 v66, v0 offset:2592
	v_mul_f32_e32 v0, 0xbfb8aa3b, v45
	v_exp_f32_e32 v0, v0
	s_nop 0
	v_add_f32_e32 v0, 1.0, v0
	v_rcp_f32_e32 v0, v0
	s_nop 0
	v_mul_f32_e32 v0, v45, v0
	v_mul_f32_e32 v0, v61, v0
	v_cvt_pk_bf16_f32 v0, v0, s0
	ds_write_b16 v66, v0 offset:2736
	v_mul_f32_e32 v0, 0xbfb8aa3b, v46
	v_exp_f32_e32 v0, v0
	s_nop 0
	v_add_f32_e32 v0, 1.0, v0
	v_rcp_f32_e32 v0, v0
	s_nop 0
	v_mul_f32_e32 v0, v46, v0
	v_mul_f32_e32 v0, v62, v0
	v_cvt_pk_bf16_f32 v0, v0, s0
	ds_write_b16 v66, v0 offset:3456
	v_mul_f32_e32 v0, 0xbfb8aa3b, v47
	v_exp_f32_e32 v0, v0
	s_nop 0
	v_add_f32_e32 v0, 1.0, v0
	v_rcp_f32_e32 v0, v0
	s_nop 0
	v_mul_f32_e32 v0, v47, v0
	v_mul_f32_e32 v0, v63, v0
	v_cvt_pk_bf16_f32 v0, v0, s0
	ds_write_b16 v66, v0 offset:3600
	v_mul_f32_e32 v0, 0xbfb8aa3b, v48
	v_exp_f32_e32 v0, v0
	s_nop 0
	v_add_f32_e32 v0, 1.0, v0
	v_rcp_f32_e32 v0, v0
	s_nop 0
	v_mul_f32_e32 v0, v48, v0
	v_mul_f32_e32 v0, v64, v0
	v_cvt_pk_bf16_f32 v0, v0, s0
	ds_write_b16 v66, v0 offset:3744
	v_mul_f32_e32 v0, 0xbfb8aa3b, v49
	v_exp_f32_e32 v0, v0
	s_nop 0
	v_add_f32_e32 v0, 1.0, v0
	v_rcp_f32_e32 v0, v0
	s_nop 0
	v_mul_f32_e32 v0, v49, v0
	v_mul_f32_e32 v0, v65, v0
	v_cvt_pk_bf16_f32 v0, v0, s0
	ds_write_b16 v66, v0 offset:3888
	v_mul_f32_e32 v0, 0xbfb8aa3b, v2
	v_exp_f32_e32 v0, v0
	s_nop 0
	v_add_f32_e32 v0, 1.0, v0
	v_rcp_f32_e32 v0, v0
	s_nop 0
	v_mul_f32_e32 v0, v2, v0
	v_mul_f32_e32 v0, v18, v0
	v_cvt_pk_bf16_f32 v0, v0, s0
	ds_write_b16 v66, v0 offset:4608
	v_mul_f32_e32 v0, 0xbfb8aa3b, v3
	v_exp_f32_e32 v0, v0
	s_nop 0
	v_add_f32_e32 v0, 1.0, v0
	v_rcp_f32_e32 v0, v0
	s_nop 0
	v_mul_f32_e32 v0, v3, v0
	v_mul_f32_e32 v0, v19, v0
	v_cvt_pk_bf16_f32 v0, v0, s0
	ds_write_b16 v66, v0 offset:4752
	v_mul_f32_e32 v0, 0xbfb8aa3b, v4
	v_exp_f32_e32 v0, v0
	s_nop 0
	v_add_f32_e32 v0, 1.0, v0
	v_rcp_f32_e32 v0, v0
	s_nop 0
	v_mul_f32_e32 v0, v4, v0
	v_mul_f32_e32 v0, v20, v0
	v_cvt_pk_bf16_f32 v0, v0, s0
	ds_write_b16 v66, v0 offset:4896
	v_mul_f32_e32 v0, 0xbfb8aa3b, v5
	v_exp_f32_e32 v0, v0
	s_nop 0
	v_add_f32_e32 v0, 1.0, v0
	v_rcp_f32_e32 v0, v0
	s_nop 0
	v_mul_f32_e32 v0, v5, v0
	v_mul_f32_e32 v0, v21, v0
	v_cvt_pk_bf16_f32 v0, v0, s0
	ds_write_b16 v66, v0 offset:5040
	v_mul_f32_e32 v0, 0xbfb8aa3b, v6
	v_exp_f32_e32 v0, v0
	s_nop 0
	v_add_f32_e32 v0, 1.0, v0
	v_rcp_f32_e32 v0, v0
	s_nop 0
	v_mul_f32_e32 v0, v6, v0
	v_mul_f32_e32 v0, v22, v0
	v_cvt_pk_bf16_f32 v0, v0, s0
	ds_write_b16 v66, v0 offset:5760
	v_mul_f32_e32 v0, 0xbfb8aa3b, v7
	v_exp_f32_e32 v0, v0
	s_nop 0
	v_add_f32_e32 v0, 1.0, v0
	v_rcp_f32_e32 v0, v0
	s_nop 0
	v_mul_f32_e32 v0, v7, v0
	v_mul_f32_e32 v0, v23, v0
	v_cvt_pk_bf16_f32 v0, v0, s0
	ds_write_b16 v66, v0 offset:5904
	v_mul_f32_e32 v0, 0xbfb8aa3b, v8
	v_exp_f32_e32 v0, v0
	s_nop 0
	v_add_f32_e32 v0, 1.0, v0
	v_rcp_f32_e32 v0, v0
	s_nop 0
	v_mul_f32_e32 v0, v8, v0
	v_mul_f32_e32 v0, v24, v0
	v_cvt_pk_bf16_f32 v0, v0, s0
	ds_write_b16 v66, v0 offset:6048
	v_mul_f32_e32 v0, 0xbfb8aa3b, v9
	v_exp_f32_e32 v0, v0
	s_nop 0
	v_add_f32_e32 v0, 1.0, v0
	v_rcp_f32_e32 v0, v0
	s_nop 0
	v_mul_f32_e32 v0, v9, v0
	v_mul_f32_e32 v0, v25, v0
	v_cvt_pk_bf16_f32 v0, v0, s0
	ds_write_b16 v66, v0 offset:6192
	v_mul_f32_e32 v0, 0xbfb8aa3b, v10
	v_exp_f32_e32 v0, v0
	s_nop 0
	v_add_f32_e32 v0, 1.0, v0
	v_rcp_f32_e32 v0, v0
	s_nop 0
	v_mul_f32_e32 v0, v10, v0
	v_mul_f32_e32 v0, v26, v0
	v_cvt_pk_bf16_f32 v0, v0, s0
	ds_write_b16 v66, v0 offset:6912
	v_mul_f32_e32 v0, 0xbfb8aa3b, v11
	v_exp_f32_e32 v0, v0
	s_nop 0
	v_add_f32_e32 v0, 1.0, v0
	v_rcp_f32_e32 v0, v0
	s_nop 0
	v_mul_f32_e32 v0, v11, v0
	v_mul_f32_e32 v0, v27, v0
	v_cvt_pk_bf16_f32 v0, v0, s0
	ds_write_b16 v66, v0 offset:7056
	v_mul_f32_e32 v0, 0xbfb8aa3b, v12
	v_exp_f32_e32 v0, v0
	s_nop 0
	v_add_f32_e32 v0, 1.0, v0
	v_rcp_f32_e32 v0, v0
	s_nop 0
	v_mul_f32_e32 v0, v12, v0
	v_mul_f32_e32 v0, v28, v0
	v_cvt_pk_bf16_f32 v0, v0, s0
	ds_write_b16 v66, v0 offset:7200
	v_mul_f32_e32 v0, 0xbfb8aa3b, v13
	v_exp_f32_e32 v0, v0
	s_nop 0
	v_add_f32_e32 v0, 1.0, v0
	v_rcp_f32_e32 v0, v0
	s_nop 0
	v_mul_f32_e32 v0, v13, v0
	v_mul_f32_e32 v0, v29, v0
	v_cvt_pk_bf16_f32 v0, v0, s0
	ds_write_b16 v66, v0 offset:7344
	v_mul_f32_e32 v0, 0xbfb8aa3b, v14
	v_exp_f32_e32 v0, v0
	s_nop 0
	v_add_f32_e32 v0, 1.0, v0
	v_rcp_f32_e32 v0, v0
	s_nop 0
	v_mul_f32_e32 v0, v14, v0
	v_mul_f32_e32 v0, v30, v0
	v_cvt_pk_bf16_f32 v0, v0, s0
	ds_write_b16 v66, v0 offset:8064
	v_mul_f32_e32 v0, 0xbfb8aa3b, v15
	v_exp_f32_e32 v0, v0
	s_nop 0
	v_add_f32_e32 v0, 1.0, v0
	v_rcp_f32_e32 v0, v0
	s_nop 0
	v_mul_f32_e32 v0, v15, v0
	v_mul_f32_e32 v0, v31, v0
	v_cvt_pk_bf16_f32 v0, v0, s0
	ds_write_b16 v66, v0 offset:8208
	v_mul_f32_e32 v0, 0xbfb8aa3b, v16
	v_exp_f32_e32 v0, v0
	s_nop 0
	v_add_f32_e32 v0, 1.0, v0
	v_rcp_f32_e32 v0, v0
	s_nop 0
	v_mul_f32_e32 v0, v16, v0
	v_mul_f32_e32 v0, v32, v0
	v_cvt_pk_bf16_f32 v0, v0, s0
	ds_write_b16 v66, v0 offset:8352
	v_mul_f32_e32 v0, 0xbfb8aa3b, v17
	v_exp_f32_e32 v0, v0
	s_nop 0
	v_add_f32_e32 v0, 1.0, v0
	v_rcp_f32_e32 v0, v0
	s_nop 0
	v_mul_f32_e32 v0, v17, v0
	v_mul_f32_e32 v0, v33, v0
	v_cvt_pk_bf16_f32 v0, v0, s0
	ds_write_b16 v66, v0 offset:8496
	v_mul_lo_u32 v0, v89, s28
	v_lshl_add_u32 v8, v88, 1, v0
	s_waitcnt lgkmcnt(0)
	s_barrier
	ds_read_b128 v[2:5], v8
	v_mul_lo_u32 v0, v89, s26
	v_add_u32_e32 v0, s23, v0
	v_or_b32_e32 v0, v0, v88
	v_add_u32_e32 v0, s99, v0
	v_lshl_add_u64 v[6:7], v[0:1], 1, s[90:91]
	s_waitcnt lgkmcnt(0)
	global_store_dwordx4 v[6:7], v[2:5], off
	ds_read_b128 v[2:5], v8 offset:4608
	v_add_u32_e32 v6, 0x16000, v0
	v_mov_b32_e32 v7, v1
	v_lshl_add_u64 v[6:7], v[6:7], 1, s[90:91]
	s_add_i32 s20, s20, s21
	s_waitcnt lgkmcnt(0)
	global_store_dwordx4 v[6:7], v[2:5], off
	ds_read_b128 v[2:5], v8 offset:9216
	v_add_u32_e32 v6, 0x2c000, v0
	v_mov_b32_e32 v7, v1
	v_lshl_add_u64 v[6:7], v[6:7], 1, s[90:91]
	v_add_u32_e32 v0, 0x42000, v0
	s_waitcnt lgkmcnt(0)
	global_store_dwordx4 v[6:7], v[2:5], off
	ds_read_b128 v[2:5], v8 offset:13824
	v_lshl_add_u64 v[6:7], v[0:1], 1, s[90:91]
	s_waitcnt lgkmcnt(0)
	global_store_dwordx4 v[6:7], v[2:5], off
	s_cmp_eq_u32 m0, 0x7ead
	s_cbranch_scc0 .Lffp_next
	s_mov_b32 m0, 0
	s_nop 1
	v_mov_b32_e32 v34, v94
	v_mov_b32_e32 v35, v95
	v_mov_b32_e32 v36, v96
	v_mov_b32_e32 v37, v97
	v_mov_b32_e32 v38, v98
	v_mov_b32_e32 v39, v99
	v_mov_b32_e32 v40, v100
	v_mov_b32_e32 v41, v101
	v_mov_b32_e32 v42, v102
	v_mov_b32_e32 v43, v103
	v_mov_b32_e32 v44, v104
	v_mov_b32_e32 v45, v105
	v_mov_b32_e32 v46, v106
	v_mov_b32_e32 v47, v107
	v_mov_b32_e32 v48, v108
	v_mov_b32_e32 v49, v109
	v_mov_b32_e32 v50, v110
	v_mov_b32_e32 v51, v111
	v_mov_b32_e32 v52, v112
	v_mov_b32_e32 v53, v113
	v_mov_b32_e32 v54, v114
	v_mov_b32_e32 v55, v115
	v_mov_b32_e32 v56, v116
	v_mov_b32_e32 v57, v117
	v_mov_b32_e32 v58, v118
	v_mov_b32_e32 v59, v119
	v_mov_b32_e32 v60, v120
	v_mov_b32_e32 v61, v121
	v_mov_b32_e32 v62, v122
	v_mov_b32_e32 v63, v123
	v_mov_b32_e32 v64, v124
	v_mov_b32_e32 v65, v125
	v_mov_b32_e32 v2, v134
	v_mov_b32_e32 v3, v135
	v_mov_b32_e32 v4, v136
	v_mov_b32_e32 v5, v137
	v_mov_b32_e32 v6, v138
	v_mov_b32_e32 v7, v139
	v_mov_b32_e32 v8, v140
	v_mov_b32_e32 v9, v141
	v_mov_b32_e32 v10, v142
	v_mov_b32_e32 v11, v143
	v_mov_b32_e32 v12, v144
	v_mov_b32_e32 v13, v145
	v_mov_b32_e32 v14, v146
	v_mov_b32_e32 v15, v147
	v_mov_b32_e32 v16, v148
	v_mov_b32_e32 v17, v149
	v_mov_b32_e32 v18, v150
	v_mov_b32_e32 v19, v151
	v_mov_b32_e32 v20, v152
	v_mov_b32_e32 v21, v153
	v_mov_b32_e32 v22, v154
	v_mov_b32_e32 v23, v155
	v_mov_b32_e32 v24, v156
	v_mov_b32_e32 v25, v157
	v_mov_b32_e32 v26, v158
	v_mov_b32_e32 v27, v159
	v_mov_b32_e32 v28, v160
	v_mov_b32_e32 v29, v161
	v_mov_b32_e32 v30, v162
	v_mov_b32_e32 v31, v163
	v_mov_b32_e32 v32, v164
	v_mov_b32_e32 v33, v165
	v_and_b32_e32 v0, 31, v90
	s_lshl_b32 s23, s98, 1
	s_add_i32 s23, s23, 1
	s_add_i32 s99, s99, 0xb00
	s_branch .Lffp_epi
.Lffp_next:
	s_add_i32 s22, s22, s81
	s_cmpk_gt_i32 s22, 0x57f
	s_cbranch_scc0 .LBB0_192
	s_movk_i32 s96, 0x48
	s_mov_b32 s19, 0x80000
	s_mov_b32 s14, 0xdb629599
	s_mov_b32 s15, 0xf534ddc0
	s_mov_b32 s16, 0xfc2757d1
	s_mov_b64 s[12:13], s[30:31]
	v_readlane_b32 s22, v255, 2
	v_readlane_b32 s23, v255, 3
